# v29 + s_setprio 1 around MFMA sections (QK, PV) in the softmax attention loops
# speedup vs baseline: 1.0011x; 1.0011x over previous
.LBB0_915:
	v_cvt_pk_bf16_f32 v166, v164, v85
	v_cvt_pk_bf16_f32 v167, v86, v87
	v_cvt_pk_bf16_f32 v168, v88, v89
	v_cvt_pk_bf16_f32 v169, v90, v165
	v_cvt_pk_bf16_f32 v86, v91, v92
	v_cvt_pk_bf16_f32 v87, v93, v94
	v_cvt_pk_bf16_f32 v88, v95, v96
	v_cvt_pk_bf16_f32 v89, v97, v98
	v_cvt_pk_bf16_f32 v68, v68, v69
	v_cvt_pk_bf16_f32 v69, v70, v71
	v_cvt_pk_bf16_f32 v70, v72, v73
	v_cvt_pk_bf16_f32 v71, v74, v84
	v_cvt_pk_bf16_f32 v72, v75, v76
	v_cvt_pk_bf16_f32 v73, v77, v78
	v_cvt_pk_bf16_f32 v74, v79, v80
	v_cvt_pk_bf16_f32 v75, v81, v82
	s_waitcnt lgkmcnt(0)
	v_add_f32_e32 v99, v83, v99
	v_fmac_f32_e32 v99, v161, v163
	s_setprio 1
	v_mfma_f32_32x32x16_bf16 v[52:67], v[166:169], v[144:147], v[52:67]
	v_mfma_f32_32x32x16_bf16 v[52:67], v[86:89], v[140:143], v[52:67]
	v_mfma_f32_32x32x16_bf16 v[52:67], v[68:71], v[136:139], v[52:67]
	v_mfma_f32_32x32x16_bf16 v[52:67], v[72:75], v[132:135], v[52:67]
	ds_read_b64_tr_b16 v[76:77], v162 offset:0x400
	ds_read_b64_tr_b16 v[78:79], v162 offset:0xc00
	ds_read_b64_tr_b16 v[80:81], v162 offset:0x1400
	ds_read_b64_tr_b16 v[82:83], v162 offset:0x1c00
	ds_read_b64_tr_b16 v[90:91], v162 offset:0x2400
	ds_read_b64_tr_b16 v[92:93], v162 offset:0x2c00
	ds_read_b64_tr_b16 v[94:95], v162 offset:0x3400
	ds_read_b64_tr_b16 v[96:97], v162 offset:0x3c00
	v_mfma_f32_32x32x16_bf16 v[36:51], v[166:169], v[128:131], v[36:51]
	v_mfma_f32_32x32x16_bf16 v[36:51], v[86:89], v[124:127], v[36:51]
	v_mfma_f32_32x32x16_bf16 v[36:51], v[68:71], v[120:123], v[36:51]
	v_mfma_f32_32x32x16_bf16 v[36:51], v[72:75], v[116:119], v[36:51]
	ds_read_b64_tr_b16 v[116:117], v162 offset:0x600
	ds_read_b64_tr_b16 v[118:119], v162 offset:0xe00
	ds_read_b64_tr_b16 v[120:121], v162 offset:0x1600
	ds_read_b64_tr_b16 v[122:123], v162 offset:0x1e00
	ds_read_b64_tr_b16 v[124:125], v162 offset:0x2600
	ds_read_b64_tr_b16 v[126:127], v162 offset:0x2e00
	ds_read_b64_tr_b16 v[128:129], v162 offset:0x3600
	ds_read_b64_tr_b16 v[130:131], v162 offset:0x3e00
	s_waitcnt lgkmcnt(8)
	v_mfma_f32_32x32x16_bf16 v[20:35], v[166:169], v[76:79], v[20:35]
	v_mfma_f32_32x32x16_bf16 v[20:35], v[86:89], v[80:83], v[20:35]
	v_mfma_f32_32x32x16_bf16 v[20:35], v[68:71], v[90:93], v[20:35]
	v_mfma_f32_32x32x16_bf16 v[20:35], v[72:75], v[94:97], v[20:35]
	s_waitcnt lgkmcnt(0)
	v_mfma_f32_32x32x16_bf16 v[4:19], v[166:169], v[116:119], v[4:19]
	s_setprio 0
	v_mov_b32_e32 v161, v99
	s_setprio 1
	v_mfma_f32_32x32x16_bf16 v[4:19], v[86:89], v[120:123], v[4:19]
	v_mfma_f32_32x32x16_bf16 v[4:19], v[68:71], v[124:127], v[4:19]
	v_mfma_f32_32x32x16_bf16 v[4:19], v[72:75], v[128:131], v[4:19]
	s_setprio 0

.LBB0_921:
	s_add_i32 s4, s33, 0xc000
	s_and_b32 s4, s4, 0xc000
	s_add_i32 s12, s4, 0
	s_add_i32 s12, s12, 0x10000
	v_add_u32_e32 v76, s12, v152
	v_add_u32_e32 v77, v76, v153
	ds_read_b128 v[68:71], v77 offset:0
	ds_read_b128 v[72:75], v77 offset:0x2000
	v_add_u32_e32 v77, v76, v155
	ds_read_b128 v[116:119], v77 offset:0
	ds_read_b128 v[120:123], v77 offset:0x2000
	v_add_u32_e32 v77, v76, v156
	ds_read_b128 v[124:127], v77 offset:0
	ds_read_b128 v[128:131], v77 offset:0x2000
	v_add_u32_e32 v76, v76, v157
	ds_read_b128 v[132:135], v76 offset:0
	ds_read_b128 v[136:139], v76 offset:0x2000
	s_waitcnt lgkmcnt(4)
	s_add_i32 s3, s2, 0xff
	s_cmp_le_u32 s3, s86
	s_setprio 1
	v_mfma_f32_32x32x16_bf16 v[84:99], v[68:71], v[100:103], 0
	v_mfma_f32_32x32x16_bf16 v[84:99], v[116:119], v[104:107], v[84:99]
	v_mfma_f32_32x32x16_bf16 v[68:83], v[72:75], v[100:103], 0
	v_mfma_f32_32x32x16_bf16 v[68:83], v[120:123], v[104:107], v[68:83]
	s_waitcnt lgkmcnt(0)
	v_mfma_f32_32x32x16_bf16 v[84:99], v[124:127], v[108:111], v[84:99]
	v_mfma_f32_32x32x16_bf16 v[84:99], v[132:135], v[112:115], v[84:99]
	v_mfma_f32_32x32x16_bf16 v[68:83], v[128:131], v[108:111], v[68:83]
	v_mfma_f32_32x32x16_bf16 v[68:83], v[136:139], v[112:115], v[68:83]
	s_setprio 0
	v_add_u32_e32 v162, s4, v158
	ds_read_b64_tr_b16 v[144:145], v162 offset:0
	ds_read_b64_tr_b16 v[146:147], v162 offset:0x800
	ds_read_b64_tr_b16 v[140:141], v162 offset:0x1000
	ds_read_b64_tr_b16 v[142:143], v162 offset:0x1800
	ds_read_b64_tr_b16 v[136:137], v162 offset:0x2000
	ds_read_b64_tr_b16 v[138:139], v162 offset:0x2800
	ds_read_b64_tr_b16 v[132:133], v162 offset:0x3000
	ds_read_b64_tr_b16 v[134:135], v162 offset:0x3800
	ds_read_b64_tr_b16 v[128:129], v162 offset:0x200
	ds_read_b64_tr_b16 v[130:131], v162 offset:0xa00
	ds_read_b64_tr_b16 v[124:125], v162 offset:0x1200
	ds_read_b64_tr_b16 v[126:127], v162 offset:0x1a00
	ds_read_b64_tr_b16 v[120:121], v162 offset:0x2200
	ds_read_b64_tr_b16 v[122:123], v162 offset:0x2a00
	ds_read_b64_tr_b16 v[116:117], v162 offset:0x3200
	ds_read_b64_tr_b16 v[118:119], v162 offset:0x3a00
	s_cbranch_scc1 .LBB0_923
	v_cmp_gt_i32_e64 s[70:71], 22, v159
	v_cmp_gt_i32_e64 s[72:73], 23, v159
	v_cmp_gt_i32_e64 s[68:69], 21, v159
	s_and_b64 s[70:71], s[72:73], s[70:71]
	v_cmp_gt_i32_e64 s[66:67], 20, v159
	s_and_b64 s[68:69], s[70:71], s[68:69]
	v_cmp_gt_i32_e64 s[64:65], 19, v159
	s_and_b64 s[66:67], s[68:69], s[66:67]
	v_cmp_gt_i32_e64 s[62:63], 18, v159
	s_and_b64 s[64:65], s[66:67], s[64:65]
	v_cmp_gt_i32_e64 s[60:61], 17, v159
	s_and_b64 s[62:63], s[64:65], s[62:63]
	v_cmp_gt_i32_e64 s[58:59], 16, v159
	s_and_b64 s[60:61], s[62:63], s[60:61]
	v_cmp_gt_i32_e64 s[56:57], 7, v159
	s_and_b64 s[58:59], s[60:61], s[58:59]
	v_cmp_gt_i32_e64 s[54:55], 6, v159
	s_and_b64 s[56:57], s[58:59], s[56:57]
	v_cmp_gt_i32_e64 s[52:53], 5, v159
	s_and_b64 s[54:55], s[56:57], s[54:55]
	v_cmp_gt_i32_e64 s[50:51], 4, v159
	s_and_b64 s[52:53], s[54:55], s[52:53]
	v_cmp_gt_i32_e64 s[48:49], 3, v159
	s_and_b64 s[50:51], s[52:53], s[50:51]
	v_cmp_gt_i32_e64 s[46:47], 2, v159
	s_and_b64 s[48:49], s[50:51], s[48:49]
	v_cmp_gt_i32_e64 s[44:45], 1, v159
	s_and_b64 s[46:47], s[48:49], s[46:47]
	v_cmp_gt_i32_e64 s[42:43], 0, v159
	s_and_b64 s[44:45], s[46:47], s[44:45]
	s_and_b64 s[42:43], s[44:45], s[42:43]
	v_cmp_gt_i32_e64 s[40:41], 54, v159
	v_cndmask_b32_e64 v84, v84, v204, s[42:43]
	v_cmp_gt_i32_e64 s[42:43], 55, v159
	v_cmp_gt_i32_e64 s[38:39], 53, v159
	s_and_b64 s[40:41], s[42:43], s[40:41]
	v_cmp_gt_i32_e64 s[36:37], 52, v159
	s_and_b64 s[38:39], s[40:41], s[38:39]
	v_cmp_gt_i32_e64 s[34:35], 51, v159
	s_and_b64 s[36:37], s[38:39], s[36:37]
	v_cmp_gt_i32_e64 s[30:31], 50, v159
	s_and_b64 s[34:35], s[36:37], s[34:35]
	v_cmp_gt_i32_e64 s[28:29], 49, v159
	s_and_b64 s[30:31], s[34:35], s[30:31]
	v_cmp_gt_i32_e64 s[26:27], 48, v159
	s_and_b64 s[28:29], s[30:31], s[28:29]
	v_cmp_gt_i32_e64 s[24:25], 39, v159
	s_and_b64 s[26:27], s[28:29], s[26:27]
	v_cmp_gt_i32_e64 s[22:23], 38, v159
	s_and_b64 s[24:25], s[26:27], s[24:25]
	v_cmp_gt_i32_e64 s[20:21], 37, v159
	s_and_b64 s[22:23], s[24:25], s[22:23]
	v_cmp_gt_i32_e64 s[18:19], 36, v159
	s_and_b64 s[20:21], s[22:23], s[20:21]
	v_cmp_gt_i32_e64 s[16:17], 35, v159
	s_and_b64 s[18:19], s[20:21], s[18:19]
	v_cmp_gt_i32_e64 s[14:15], 34, v159
	s_and_b64 s[16:17], s[18:19], s[16:17]
	v_cmp_gt_i32_e64 s[12:13], 33, v159
	s_and_b64 s[14:15], s[16:17], s[14:15]
	v_cmp_gt_i32_e32 vcc, 32, v159
	s_and_b64 s[12:13], s[14:15], s[12:13]
	s_and_b64 vcc, s[12:13], vcc
	v_cndmask_b32_e64 v99, v99, v204, s[72:73]
	v_cndmask_b32_e64 v98, v98, v204, s[70:71]
	v_cndmask_b32_e64 v97, v97, v204, s[68:69]
	v_cndmask_b32_e64 v96, v96, v204, s[66:67]
	v_cndmask_b32_e64 v95, v95, v204, s[64:65]
	v_cndmask_b32_e64 v94, v94, v204, s[62:63]
	v_cndmask_b32_e64 v93, v93, v204, s[60:61]
	v_cndmask_b32_e64 v92, v92, v204, s[58:59]
	v_cndmask_b32_e64 v91, v91, v204, s[56:57]
	v_cndmask_b32_e64 v90, v90, v204, s[54:55]
	v_cndmask_b32_e64 v89, v89, v204, s[52:53]
	v_cndmask_b32_e64 v88, v88, v204, s[50:51]
	v_cndmask_b32_e64 v87, v87, v204, s[48:49]
	v_cndmask_b32_e64 v86, v86, v204, s[46:47]
	v_cndmask_b32_e64 v85, v85, v204, s[44:45]
	v_cndmask_b32_e64 v83, v83, v204, s[42:43]
	v_cndmask_b32_e64 v82, v82, v204, s[40:41]
	v_cndmask_b32_e64 v81, v81, v204, s[38:39]
	v_cndmask_b32_e64 v80, v80, v204, s[36:37]
	v_cndmask_b32_e64 v79, v79, v204, s[34:35]
	v_cndmask_b32_e64 v78, v78, v204, s[30:31]
	v_cndmask_b32_e64 v77, v77, v204, s[28:29]
	v_cndmask_b32_e64 v76, v76, v204, s[26:27]
	v_cndmask_b32_e64 v75, v75, v204, s[24:25]
	v_cndmask_b32_e64 v74, v74, v204, s[22:23]
	v_cndmask_b32_e64 v73, v73, v204, s[20:21]
	v_cndmask_b32_e64 v72, v72, v204, s[18:19]
	v_cndmask_b32_e64 v71, v71, v204, s[16:17]
	v_cndmask_b32_e64 v70, v70, v204, s[14:15]
	v_cndmask_b32_e64 v69, v69, v204, s[12:13]
	v_cndmask_b32_e32 v68, v68, v204, vcc

.LBB0_928:
	v_cvt_pk_bf16_f32 v166, v164, v85
	v_cvt_pk_bf16_f32 v167, v86, v87
	v_cvt_pk_bf16_f32 v168, v88, v89
	v_cvt_pk_bf16_f32 v169, v90, v165
	v_cvt_pk_bf16_f32 v86, v91, v92
	v_cvt_pk_bf16_f32 v87, v93, v94
	v_cvt_pk_bf16_f32 v88, v95, v96
	v_cvt_pk_bf16_f32 v89, v97, v98
	v_cvt_pk_bf16_f32 v68, v68, v69
	v_cvt_pk_bf16_f32 v69, v70, v71
	v_cvt_pk_bf16_f32 v70, v72, v73
	v_cvt_pk_bf16_f32 v71, v74, v84
	v_cvt_pk_bf16_f32 v72, v75, v76
	v_cvt_pk_bf16_f32 v73, v77, v78
	v_cvt_pk_bf16_f32 v74, v79, v80
	v_cvt_pk_bf16_f32 v75, v81, v82
	s_waitcnt lgkmcnt(0)
	v_add_f32_e32 v99, v83, v99
	v_fmac_f32_e32 v99, v161, v163
	s_setprio 1
	v_mfma_f32_32x32x16_bf16 v[52:67], v[166:169], v[144:147], v[52:67]
	v_mfma_f32_32x32x16_bf16 v[52:67], v[86:89], v[140:143], v[52:67]
	v_mfma_f32_32x32x16_bf16 v[52:67], v[68:71], v[136:139], v[52:67]
	v_mfma_f32_32x32x16_bf16 v[52:67], v[72:75], v[132:135], v[52:67]
	ds_read_b64_tr_b16 v[76:77], v162 offset:0x400
	ds_read_b64_tr_b16 v[78:79], v162 offset:0xc00
	ds_read_b64_tr_b16 v[80:81], v162 offset:0x1400
	ds_read_b64_tr_b16 v[82:83], v162 offset:0x1c00
	ds_read_b64_tr_b16 v[90:91], v162 offset:0x2400
	ds_read_b64_tr_b16 v[92:93], v162 offset:0x2c00
	ds_read_b64_tr_b16 v[94:95], v162 offset:0x3400
	ds_read_b64_tr_b16 v[96:97], v162 offset:0x3c00
	v_mfma_f32_32x32x16_bf16 v[36:51], v[166:169], v[128:131], v[36:51]
	v_mfma_f32_32x32x16_bf16 v[36:51], v[86:89], v[124:127], v[36:51]
	v_mfma_f32_32x32x16_bf16 v[36:51], v[68:71], v[120:123], v[36:51]
	v_mfma_f32_32x32x16_bf16 v[36:51], v[72:75], v[116:119], v[36:51]
	ds_read_b64_tr_b16 v[116:117], v162 offset:0x600
	ds_read_b64_tr_b16 v[118:119], v162 offset:0xe00
	ds_read_b64_tr_b16 v[120:121], v162 offset:0x1600
	ds_read_b64_tr_b16 v[122:123], v162 offset:0x1e00
	ds_read_b64_tr_b16 v[124:125], v162 offset:0x2600
	ds_read_b64_tr_b16 v[126:127], v162 offset:0x2e00
	ds_read_b64_tr_b16 v[128:129], v162 offset:0x3600
	ds_read_b64_tr_b16 v[130:131], v162 offset:0x3e00
	s_waitcnt lgkmcnt(8)
	v_mfma_f32_32x32x16_bf16 v[20:35], v[166:169], v[76:79], v[20:35]
	v_mfma_f32_32x32x16_bf16 v[20:35], v[86:89], v[80:83], v[20:35]
	v_mfma_f32_32x32x16_bf16 v[20:35], v[68:71], v[90:93], v[20:35]
	v_mfma_f32_32x32x16_bf16 v[20:35], v[72:75], v[94:97], v[20:35]
	s_waitcnt lgkmcnt(0)
	v_mfma_f32_32x32x16_bf16 v[4:19], v[166:169], v[116:119], v[4:19]
	s_setprio 0
	v_mov_b32_e32 v161, v99
	s_setprio 1
	v_mfma_f32_32x32x16_bf16 v[4:19], v[86:89], v[120:123], v[4:19]
	v_mfma_f32_32x32x16_bf16 v[4:19], v[68:71], v[124:127], v[4:19]
	v_mfma_f32_32x32x16_bf16 v[4:19], v[72:75], v[128:131], v[4:19]
	s_setprio 0
	s_add_i32 s3, s2, 0x80
	s_cmp_gt_i32 s3, s90
	s_cbranch_scc1 .LBB0_916
.LBB0_929:
	s_add_i32 s4, s33, 0x8000
	s_and_b32 s4, s4, 0xc000
	s_add_i32 s12, s4, 0
	s_add_i32 s12, s12, 0x10000
	v_add_u32_e32 v76, s12, v152
	v_add_u32_e32 v77, v76, v153
	ds_read_b128 v[68:71], v77 offset:0
	ds_read_b128 v[72:75], v77 offset:0x2000
	v_add_u32_e32 v77, v76, v155
	ds_read_b128 v[116:119], v77 offset:0
	ds_read_b128 v[120:123], v77 offset:0x2000
	v_add_u32_e32 v77, v76, v156
	ds_read_b128 v[124:127], v77 offset:0
	ds_read_b128 v[128:131], v77 offset:0x2000
	v_add_u32_e32 v76, v76, v157
	ds_read_b128 v[132:135], v76 offset:0
	ds_read_b128 v[136:139], v76 offset:0x2000
	s_waitcnt lgkmcnt(4)
	s_add_i32 s3, s2, 0xbf
	s_cmp_le_i32 s3, s86
	s_setprio 1
	v_mfma_f32_32x32x16_bf16 v[84:99], v[68:71], v[100:103], 0
	v_mfma_f32_32x32x16_bf16 v[84:99], v[116:119], v[104:107], v[84:99]
	v_mfma_f32_32x32x16_bf16 v[68:83], v[72:75], v[100:103], 0
	v_mfma_f32_32x32x16_bf16 v[68:83], v[120:123], v[104:107], v[68:83]
	s_waitcnt lgkmcnt(0)
	v_mfma_f32_32x32x16_bf16 v[84:99], v[124:127], v[108:111], v[84:99]
	v_mfma_f32_32x32x16_bf16 v[84:99], v[132:135], v[112:115], v[84:99]
	v_mfma_f32_32x32x16_bf16 v[68:83], v[128:131], v[108:111], v[68:83]
	v_mfma_f32_32x32x16_bf16 v[68:83], v[136:139], v[112:115], v[68:83]
	s_setprio 0
	v_add_u32_e32 v162, s4, v158
	ds_read_b64_tr_b16 v[144:145], v162 offset:0
	ds_read_b64_tr_b16 v[146:147], v162 offset:0x800
	ds_read_b64_tr_b16 v[140:141], v162 offset:0x1000
	ds_read_b64_tr_b16 v[142:143], v162 offset:0x1800
	ds_read_b64_tr_b16 v[136:137], v162 offset:0x2000
	ds_read_b64_tr_b16 v[138:139], v162 offset:0x2800
	ds_read_b64_tr_b16 v[132:133], v162 offset:0x3000
	ds_read_b64_tr_b16 v[134:135], v162 offset:0x3800
	ds_read_b64_tr_b16 v[128:129], v162 offset:0x200
	ds_read_b64_tr_b16 v[130:131], v162 offset:0xa00
	ds_read_b64_tr_b16 v[124:125], v162 offset:0x1200
	ds_read_b64_tr_b16 v[126:127], v162 offset:0x1a00
	ds_read_b64_tr_b16 v[120:121], v162 offset:0x2200
	ds_read_b64_tr_b16 v[122:123], v162 offset:0x2a00
	ds_read_b64_tr_b16 v[116:117], v162 offset:0x3200
	ds_read_b64_tr_b16 v[118:119], v162 offset:0x3a00
	s_cbranch_scc1 .LBB0_931
	v_add_u32_e32 v163, 64, v159
	v_cmp_gt_i32_e64 s[70:71], 22, v163
	v_cmp_gt_i32_e64 s[72:73], 23, v163
	v_cmp_gt_i32_e64 s[68:69], 21, v163
	s_and_b64 s[70:71], s[72:73], s[70:71]
	v_cmp_gt_i32_e64 s[66:67], 20, v163
	s_and_b64 s[68:69], s[70:71], s[68:69]
	v_cmp_gt_i32_e64 s[64:65], 19, v163
	s_and_b64 s[66:67], s[68:69], s[66:67]
	v_cmp_gt_i32_e64 s[62:63], 18, v163
	s_and_b64 s[64:65], s[66:67], s[64:65]
	v_cmp_gt_i32_e64 s[60:61], 17, v163
	s_and_b64 s[62:63], s[64:65], s[62:63]
	v_cmp_gt_i32_e64 s[58:59], 16, v163
	s_and_b64 s[60:61], s[62:63], s[60:61]
	v_cmp_gt_i32_e64 s[56:57], 7, v163
	s_and_b64 s[58:59], s[60:61], s[58:59]
	v_cmp_gt_i32_e64 s[54:55], 6, v163
	s_and_b64 s[56:57], s[58:59], s[56:57]
	v_cmp_gt_i32_e64 s[52:53], 5, v163
	s_and_b64 s[54:55], s[56:57], s[54:55]
	v_cmp_gt_i32_e64 s[50:51], 4, v163
	s_and_b64 s[52:53], s[54:55], s[52:53]
	v_cmp_gt_i32_e64 s[48:49], 3, v163
	s_and_b64 s[50:51], s[52:53], s[50:51]
	v_cmp_gt_i32_e64 s[46:47], 2, v163
	s_and_b64 s[48:49], s[50:51], s[48:49]
	v_cmp_gt_i32_e64 s[44:45], 1, v163
	s_and_b64 s[46:47], s[48:49], s[46:47]
	v_cmp_gt_i32_e64 s[42:43], 0, v163
	s_and_b64 s[44:45], s[46:47], s[44:45]
	s_and_b64 s[42:43], s[44:45], s[42:43]
	v_cmp_gt_i32_e64 s[40:41], 54, v163
	v_cndmask_b32_e64 v84, v84, v204, s[42:43]
	v_cmp_gt_i32_e64 s[42:43], 55, v163
	v_cmp_gt_i32_e64 s[38:39], 53, v163
	s_and_b64 s[40:41], s[42:43], s[40:41]
	v_cmp_gt_i32_e64 s[36:37], 52, v163
	s_and_b64 s[38:39], s[40:41], s[38:39]
	v_cmp_gt_i32_e64 s[34:35], 51, v163
	s_and_b64 s[36:37], s[38:39], s[36:37]
	v_cmp_gt_i32_e64 s[30:31], 50, v163
	s_and_b64 s[34:35], s[36:37], s[34:35]
	v_cmp_gt_i32_e64 s[28:29], 49, v163
	s_and_b64 s[30:31], s[34:35], s[30:31]
	v_cmp_gt_i32_e64 s[26:27], 48, v163
	s_and_b64 s[28:29], s[30:31], s[28:29]
	v_cmp_gt_i32_e64 s[24:25], 39, v163
	s_and_b64 s[26:27], s[28:29], s[26:27]
	v_cmp_gt_i32_e64 s[22:23], 38, v163
	s_and_b64 s[24:25], s[26:27], s[24:25]
	v_cmp_gt_i32_e64 s[20:21], 37, v163
	s_and_b64 s[22:23], s[24:25], s[22:23]
	v_cmp_gt_i32_e64 s[18:19], 36, v163
	s_and_b64 s[20:21], s[22:23], s[20:21]
	v_cmp_gt_i32_e64 s[16:17], 35, v163
	s_and_b64 s[18:19], s[20:21], s[18:19]
	v_cmp_gt_i32_e64 s[14:15], 34, v163
	s_and_b64 s[16:17], s[18:19], s[16:17]
	v_cmp_gt_i32_e64 s[12:13], 33, v163
	s_and_b64 s[14:15], s[16:17], s[14:15]
	v_cmp_gt_i32_e32 vcc, 32, v163
	s_and_b64 s[12:13], s[14:15], s[12:13]
	s_and_b64 vcc, s[12:13], vcc
	v_cndmask_b32_e64 v99, v99, v204, s[72:73]
	v_cndmask_b32_e64 v98, v98, v204, s[70:71]
	v_cndmask_b32_e64 v97, v97, v204, s[68:69]
	v_cndmask_b32_e64 v96, v96, v204, s[66:67]
	v_cndmask_b32_e64 v95, v95, v204, s[64:65]
	v_cndmask_b32_e64 v94, v94, v204, s[62:63]
	v_cndmask_b32_e64 v93, v93, v204, s[60:61]
	v_cndmask_b32_e64 v92, v92, v204, s[58:59]
	v_cndmask_b32_e64 v91, v91, v204, s[56:57]
	v_cndmask_b32_e64 v90, v90, v204, s[54:55]
	v_cndmask_b32_e64 v89, v89, v204, s[52:53]
	v_cndmask_b32_e64 v88, v88, v204, s[50:51]
	v_cndmask_b32_e64 v87, v87, v204, s[48:49]
	v_cndmask_b32_e64 v86, v86, v204, s[46:47]
	v_cndmask_b32_e64 v85, v85, v204, s[44:45]
	v_cndmask_b32_e64 v83, v83, v204, s[42:43]
	v_cndmask_b32_e64 v82, v82, v204, s[40:41]
	v_cndmask_b32_e64 v81, v81, v204, s[38:39]
	v_cndmask_b32_e64 v80, v80, v204, s[36:37]
	v_cndmask_b32_e64 v79, v79, v204, s[34:35]
	v_cndmask_b32_e64 v78, v78, v204, s[30:31]
	v_cndmask_b32_e64 v77, v77, v204, s[28:29]
	v_cndmask_b32_e64 v76, v76, v204, s[26:27]
	v_cndmask_b32_e64 v75, v75, v204, s[24:25]
	v_cndmask_b32_e64 v74, v74, v204, s[22:23]
	v_cndmask_b32_e64 v73, v73, v204, s[20:21]
	v_cndmask_b32_e64 v72, v72, v204, s[18:19]
	v_cndmask_b32_e64 v71, v71, v204, s[16:17]
	v_cndmask_b32_e64 v70, v70, v204, s[14:15]
	v_cndmask_b32_e64 v69, v69, v204, s[12:13]
	v_cndmask_b32_e32 v68, v68, v204, vcc

.LBB0_941:
	v_cvt_pk_bf16_f32 v168, v166, v85
	v_cvt_pk_bf16_f32 v169, v86, v87
	v_cvt_pk_bf16_f32 v170, v88, v89
	v_cvt_pk_bf16_f32 v171, v90, v167
	v_cvt_pk_bf16_f32 v86, v91, v92
	v_cvt_pk_bf16_f32 v87, v93, v94
	v_cvt_pk_bf16_f32 v88, v95, v96
	v_cvt_pk_bf16_f32 v89, v97, v98
	v_cvt_pk_bf16_f32 v68, v68, v69
	v_cvt_pk_bf16_f32 v69, v70, v71
	v_cvt_pk_bf16_f32 v70, v72, v73
	v_cvt_pk_bf16_f32 v71, v74, v84
	v_cvt_pk_bf16_f32 v72, v75, v76
	v_cvt_pk_bf16_f32 v73, v77, v78
	v_cvt_pk_bf16_f32 v74, v79, v80
	v_cvt_pk_bf16_f32 v75, v81, v82
	s_waitcnt lgkmcnt(0)
	v_add_f32_e32 v99, v83, v99
	v_fmac_f32_e32 v99, v163, v165
	s_setprio 1
	v_mfma_f32_32x32x16_bf16 v[52:67], v[168:171], v[144:147], v[52:67]
	v_mfma_f32_32x32x16_bf16 v[52:67], v[86:89], v[140:143], v[52:67]
	v_mfma_f32_32x32x16_bf16 v[52:67], v[68:71], v[136:139], v[52:67]
	v_mfma_f32_32x32x16_bf16 v[52:67], v[72:75], v[132:135], v[52:67]
	ds_read_b64_tr_b16 v[76:77], v164 offset:0x400
	ds_read_b64_tr_b16 v[78:79], v164 offset:0xc00
	ds_read_b64_tr_b16 v[80:81], v164 offset:0x1400
	ds_read_b64_tr_b16 v[82:83], v164 offset:0x1c00
	ds_read_b64_tr_b16 v[90:91], v164 offset:0x2400
	ds_read_b64_tr_b16 v[92:93], v164 offset:0x2c00
	ds_read_b64_tr_b16 v[94:95], v164 offset:0x3400
	ds_read_b64_tr_b16 v[96:97], v164 offset:0x3c00
	v_mfma_f32_32x32x16_bf16 v[36:51], v[168:171], v[128:131], v[36:51]
	v_mfma_f32_32x32x16_bf16 v[36:51], v[86:89], v[124:127], v[36:51]
	v_mfma_f32_32x32x16_bf16 v[36:51], v[68:71], v[120:123], v[36:51]
	v_mfma_f32_32x32x16_bf16 v[36:51], v[72:75], v[116:119], v[36:51]
	ds_read_b64_tr_b16 v[116:117], v164 offset:0x600
	ds_read_b64_tr_b16 v[118:119], v164 offset:0xe00
	ds_read_b64_tr_b16 v[120:121], v164 offset:0x1600
	ds_read_b64_tr_b16 v[122:123], v164 offset:0x1e00
	ds_read_b64_tr_b16 v[124:125], v164 offset:0x2600
	ds_read_b64_tr_b16 v[126:127], v164 offset:0x2e00
	ds_read_b64_tr_b16 v[128:129], v164 offset:0x3600
	ds_read_b64_tr_b16 v[130:131], v164 offset:0x3e00
	s_waitcnt lgkmcnt(8)
	v_mfma_f32_32x32x16_bf16 v[20:35], v[168:171], v[76:79], v[20:35]
	v_mfma_f32_32x32x16_bf16 v[20:35], v[86:89], v[80:83], v[20:35]
	v_mfma_f32_32x32x16_bf16 v[20:35], v[68:71], v[90:93], v[20:35]
	v_mfma_f32_32x32x16_bf16 v[20:35], v[72:75], v[94:97], v[20:35]
	s_waitcnt lgkmcnt(0)
	v_mfma_f32_32x32x16_bf16 v[4:19], v[168:171], v[116:119], v[4:19]
	s_setprio 0
	v_mov_b32_e32 v163, v99
	s_setprio 1
	v_mfma_f32_32x32x16_bf16 v[4:19], v[86:89], v[120:123], v[4:19]
	v_mfma_f32_32x32x16_bf16 v[4:19], v[68:71], v[124:127], v[4:19]
	v_mfma_f32_32x32x16_bf16 v[4:19], v[72:75], v[128:131], v[4:19]
	s_setprio 0

.LBB0_947:
	s_add_i32 s4, s0, 0xc000
	s_and_b32 s4, s4, 0xc000
	s_add_i32 s12, s4, 0
	s_add_i32 s12, s12, 0x10000
	v_add_u32_e32 v76, s12, v154
	v_add_u32_e32 v77, v76, v156
	ds_read_b128 v[68:71], v77 offset:0
	ds_read_b128 v[72:75], v77 offset:0x2000
	v_add_u32_e32 v77, v76, v157
	ds_read_b128 v[116:119], v77 offset:0
	ds_read_b128 v[120:123], v77 offset:0x2000
	v_add_u32_e32 v77, v76, v158
	ds_read_b128 v[124:127], v77 offset:0
	ds_read_b128 v[128:131], v77 offset:0x2000
	v_add_u32_e32 v76, v76, v159
	ds_read_b128 v[132:135], v76 offset:0
	ds_read_b128 v[136:139], v76 offset:0x2000
	s_waitcnt lgkmcnt(4)
	s_add_i32 s3, s2, 0xff
	s_cmp_le_u32 s3, s79
	s_setprio 1
	v_mfma_f32_32x32x16_bf16 v[84:99], v[68:71], v[100:103], 0
	v_mfma_f32_32x32x16_bf16 v[84:99], v[116:119], v[104:107], v[84:99]
	v_mfma_f32_32x32x16_bf16 v[68:83], v[72:75], v[100:103], 0
	v_mfma_f32_32x32x16_bf16 v[68:83], v[120:123], v[104:107], v[68:83]
	s_waitcnt lgkmcnt(0)
	v_mfma_f32_32x32x16_bf16 v[84:99], v[124:127], v[108:111], v[84:99]
	v_mfma_f32_32x32x16_bf16 v[84:99], v[132:135], v[112:115], v[84:99]
	v_mfma_f32_32x32x16_bf16 v[68:83], v[128:131], v[108:111], v[68:83]
	v_mfma_f32_32x32x16_bf16 v[68:83], v[136:139], v[112:115], v[68:83]
	s_setprio 0
	v_add_u32_e32 v164, s4, v160
	ds_read_b64_tr_b16 v[144:145], v164 offset:0
	ds_read_b64_tr_b16 v[146:147], v164 offset:0x800
	ds_read_b64_tr_b16 v[140:141], v164 offset:0x1000
	ds_read_b64_tr_b16 v[142:143], v164 offset:0x1800
	ds_read_b64_tr_b16 v[136:137], v164 offset:0x2000
	ds_read_b64_tr_b16 v[138:139], v164 offset:0x2800
	ds_read_b64_tr_b16 v[132:133], v164 offset:0x3000
	ds_read_b64_tr_b16 v[134:135], v164 offset:0x3800
	ds_read_b64_tr_b16 v[128:129], v164 offset:0x200
	ds_read_b64_tr_b16 v[130:131], v164 offset:0xa00
	ds_read_b64_tr_b16 v[124:125], v164 offset:0x1200
	ds_read_b64_tr_b16 v[126:127], v164 offset:0x1a00
	ds_read_b64_tr_b16 v[120:121], v164 offset:0x2200
	ds_read_b64_tr_b16 v[122:123], v164 offset:0x2a00
	ds_read_b64_tr_b16 v[116:117], v164 offset:0x3200
	ds_read_b64_tr_b16 v[118:119], v164 offset:0x3a00
	s_cbranch_scc1 .LBB0_949
	v_cmp_gt_i32_e64 s[70:71], 22, v161
	v_cmp_gt_i32_e64 s[72:73], 23, v161
	v_cmp_gt_i32_e64 s[68:69], 21, v161
	s_and_b64 s[70:71], s[72:73], s[70:71]
	v_cmp_gt_i32_e64 s[66:67], 20, v161
	s_and_b64 s[68:69], s[70:71], s[68:69]
	v_cmp_gt_i32_e64 s[64:65], 19, v161
	s_and_b64 s[66:67], s[68:69], s[66:67]
	v_cmp_gt_i32_e64 s[62:63], 18, v161
	s_and_b64 s[64:65], s[66:67], s[64:65]
	v_cmp_gt_i32_e64 s[60:61], 17, v161
	s_and_b64 s[62:63], s[64:65], s[62:63]
	v_cmp_gt_i32_e64 s[58:59], 16, v161
	s_and_b64 s[60:61], s[62:63], s[60:61]
	v_cmp_gt_i32_e64 s[56:57], 7, v161
	s_and_b64 s[58:59], s[60:61], s[58:59]
	v_cmp_gt_i32_e64 s[54:55], 6, v161
	s_and_b64 s[56:57], s[58:59], s[56:57]
	v_cmp_gt_i32_e64 s[52:53], 5, v161
	s_and_b64 s[54:55], s[56:57], s[54:55]
	v_cmp_gt_i32_e64 s[50:51], 4, v161
	s_and_b64 s[52:53], s[54:55], s[52:53]
	v_cmp_gt_i32_e64 s[48:49], 3, v161
	s_and_b64 s[50:51], s[52:53], s[50:51]
	v_cmp_gt_i32_e64 s[46:47], 2, v161
	s_and_b64 s[48:49], s[50:51], s[48:49]
	v_cmp_gt_i32_e64 s[44:45], 1, v161
	s_and_b64 s[46:47], s[48:49], s[46:47]
	v_cmp_gt_i32_e64 s[42:43], 0, v161
	s_and_b64 s[44:45], s[46:47], s[44:45]
	s_and_b64 s[42:43], s[44:45], s[42:43]
	v_cmp_gt_i32_e64 s[40:41], 54, v161
	v_cndmask_b32_e64 v84, v84, v204, s[42:43]
	v_cmp_gt_i32_e64 s[42:43], 55, v161
	v_cmp_gt_i32_e64 s[38:39], 53, v161
	s_and_b64 s[40:41], s[42:43], s[40:41]
	v_cmp_gt_i32_e64 s[36:37], 52, v161
	s_and_b64 s[38:39], s[40:41], s[38:39]
	v_cmp_gt_i32_e64 s[34:35], 51, v161
	s_and_b64 s[36:37], s[38:39], s[36:37]
	v_cmp_gt_i32_e64 s[30:31], 50, v161
	s_and_b64 s[34:35], s[36:37], s[34:35]
	v_cmp_gt_i32_e64 s[28:29], 49, v161
	s_and_b64 s[30:31], s[34:35], s[30:31]
	v_cmp_gt_i32_e64 s[26:27], 48, v161
	s_and_b64 s[28:29], s[30:31], s[28:29]
	v_cmp_gt_i32_e64 s[24:25], 39, v161
	s_and_b64 s[26:27], s[28:29], s[26:27]
	v_cmp_gt_i32_e64 s[22:23], 38, v161
	s_and_b64 s[24:25], s[26:27], s[24:25]
	v_cmp_gt_i32_e64 s[20:21], 37, v161
	s_and_b64 s[22:23], s[24:25], s[22:23]
	v_cmp_gt_i32_e64 s[18:19], 36, v161
	s_and_b64 s[20:21], s[22:23], s[20:21]
	v_cmp_gt_i32_e64 s[16:17], 35, v161
	s_and_b64 s[18:19], s[20:21], s[18:19]
	v_cmp_gt_i32_e64 s[14:15], 34, v161
	s_and_b64 s[16:17], s[18:19], s[16:17]
	v_cmp_gt_i32_e64 s[12:13], 33, v161
	s_and_b64 s[14:15], s[16:17], s[14:15]
	v_cmp_gt_i32_e32 vcc, 32, v161
	s_and_b64 s[12:13], s[14:15], s[12:13]
	s_and_b64 vcc, s[12:13], vcc
	v_cndmask_b32_e64 v99, v99, v204, s[72:73]
	v_cndmask_b32_e64 v98, v98, v204, s[70:71]
	v_cndmask_b32_e64 v97, v97, v204, s[68:69]
	v_cndmask_b32_e64 v96, v96, v204, s[66:67]
	v_cndmask_b32_e64 v95, v95, v204, s[64:65]
	v_cndmask_b32_e64 v94, v94, v204, s[62:63]
	v_cndmask_b32_e64 v93, v93, v204, s[60:61]
	v_cndmask_b32_e64 v92, v92, v204, s[58:59]
	v_cndmask_b32_e64 v91, v91, v204, s[56:57]
	v_cndmask_b32_e64 v90, v90, v204, s[54:55]
	v_cndmask_b32_e64 v89, v89, v204, s[52:53]
	v_cndmask_b32_e64 v88, v88, v204, s[50:51]
	v_cndmask_b32_e64 v87, v87, v204, s[48:49]
	v_cndmask_b32_e64 v86, v86, v204, s[46:47]
	v_cndmask_b32_e64 v85, v85, v204, s[44:45]
	v_cndmask_b32_e64 v83, v83, v204, s[42:43]
	v_cndmask_b32_e64 v82, v82, v204, s[40:41]
	v_cndmask_b32_e64 v81, v81, v204, s[38:39]
	v_cndmask_b32_e64 v80, v80, v204, s[36:37]
	v_cndmask_b32_e64 v79, v79, v204, s[34:35]
	v_cndmask_b32_e64 v78, v78, v204, s[30:31]
	v_cndmask_b32_e64 v77, v77, v204, s[28:29]
	v_cndmask_b32_e64 v76, v76, v204, s[26:27]
	v_cndmask_b32_e64 v75, v75, v204, s[24:25]
	v_cndmask_b32_e64 v74, v74, v204, s[22:23]
	v_cndmask_b32_e64 v73, v73, v204, s[20:21]
	v_cndmask_b32_e64 v72, v72, v204, s[18:19]
	v_cndmask_b32_e64 v71, v71, v204, s[16:17]
	v_cndmask_b32_e64 v70, v70, v204, s[14:15]
	v_cndmask_b32_e64 v69, v69, v204, s[12:13]
	v_cndmask_b32_e32 v68, v68, v204, vcc

.LBB0_954:
	v_cvt_pk_bf16_f32 v168, v166, v85
	v_cvt_pk_bf16_f32 v169, v86, v87
	v_cvt_pk_bf16_f32 v170, v88, v89
	v_cvt_pk_bf16_f32 v171, v90, v167
	v_cvt_pk_bf16_f32 v86, v91, v92
	v_cvt_pk_bf16_f32 v87, v93, v94
	v_cvt_pk_bf16_f32 v88, v95, v96
	v_cvt_pk_bf16_f32 v89, v97, v98
	v_cvt_pk_bf16_f32 v68, v68, v69
	v_cvt_pk_bf16_f32 v69, v70, v71
	v_cvt_pk_bf16_f32 v70, v72, v73
	v_cvt_pk_bf16_f32 v71, v74, v84
	v_cvt_pk_bf16_f32 v72, v75, v76
	v_cvt_pk_bf16_f32 v73, v77, v78
	v_cvt_pk_bf16_f32 v74, v79, v80
	v_cvt_pk_bf16_f32 v75, v81, v82
	s_waitcnt lgkmcnt(0)
	v_add_f32_e32 v99, v83, v99
	v_fmac_f32_e32 v99, v163, v165
	s_setprio 1
	v_mfma_f32_32x32x16_bf16 v[52:67], v[168:171], v[144:147], v[52:67]
	v_mfma_f32_32x32x16_bf16 v[52:67], v[86:89], v[140:143], v[52:67]
	v_mfma_f32_32x32x16_bf16 v[52:67], v[68:71], v[136:139], v[52:67]
	v_mfma_f32_32x32x16_bf16 v[52:67], v[72:75], v[132:135], v[52:67]
	ds_read_b64_tr_b16 v[76:77], v164 offset:0x400
	ds_read_b64_tr_b16 v[78:79], v164 offset:0xc00
	ds_read_b64_tr_b16 v[80:81], v164 offset:0x1400
	ds_read_b64_tr_b16 v[82:83], v164 offset:0x1c00
	ds_read_b64_tr_b16 v[90:91], v164 offset:0x2400
	ds_read_b64_tr_b16 v[92:93], v164 offset:0x2c00
	ds_read_b64_tr_b16 v[94:95], v164 offset:0x3400
	ds_read_b64_tr_b16 v[96:97], v164 offset:0x3c00
	v_mfma_f32_32x32x16_bf16 v[36:51], v[168:171], v[128:131], v[36:51]
	v_mfma_f32_32x32x16_bf16 v[36:51], v[86:89], v[124:127], v[36:51]
	v_mfma_f32_32x32x16_bf16 v[36:51], v[68:71], v[120:123], v[36:51]
	v_mfma_f32_32x32x16_bf16 v[36:51], v[72:75], v[116:119], v[36:51]
	ds_read_b64_tr_b16 v[116:117], v164 offset:0x600
	ds_read_b64_tr_b16 v[118:119], v164 offset:0xe00
	ds_read_b64_tr_b16 v[120:121], v164 offset:0x1600
	ds_read_b64_tr_b16 v[122:123], v164 offset:0x1e00
	ds_read_b64_tr_b16 v[124:125], v164 offset:0x2600
	ds_read_b64_tr_b16 v[126:127], v164 offset:0x2e00
	ds_read_b64_tr_b16 v[128:129], v164 offset:0x3600
	ds_read_b64_tr_b16 v[130:131], v164 offset:0x3e00
	s_waitcnt lgkmcnt(8)
	v_mfma_f32_32x32x16_bf16 v[20:35], v[168:171], v[76:79], v[20:35]
	v_mfma_f32_32x32x16_bf16 v[20:35], v[86:89], v[80:83], v[20:35]
	v_mfma_f32_32x32x16_bf16 v[20:35], v[68:71], v[90:93], v[20:35]
	v_mfma_f32_32x32x16_bf16 v[20:35], v[72:75], v[94:97], v[20:35]
	s_waitcnt lgkmcnt(0)
	v_mfma_f32_32x32x16_bf16 v[4:19], v[168:171], v[116:119], v[4:19]
	s_setprio 0
	v_mov_b32_e32 v163, v99
	s_setprio 1
	v_mfma_f32_32x32x16_bf16 v[4:19], v[86:89], v[120:123], v[4:19]
	v_mfma_f32_32x32x16_bf16 v[4:19], v[68:71], v[124:127], v[4:19]
	v_mfma_f32_32x32x16_bf16 v[4:19], v[72:75], v[128:131], v[4:19]
	s_setprio 0
	s_add_i32 s3, s2, 0x80
	s_cmp_gt_i32 s3, s80
	s_cbranch_scc1 .LBB0_942
.LBB0_955:
	s_add_i32 s4, s0, 0x8000
	s_and_b32 s4, s4, 0xc000
	s_add_i32 s12, s4, 0
	s_add_i32 s12, s12, 0x10000
	v_add_u32_e32 v76, s12, v154
	v_add_u32_e32 v77, v76, v156
	ds_read_b128 v[68:71], v77 offset:0
	ds_read_b128 v[72:75], v77 offset:0x2000
	v_add_u32_e32 v77, v76, v157
	ds_read_b128 v[116:119], v77 offset:0
	ds_read_b128 v[120:123], v77 offset:0x2000
	v_add_u32_e32 v77, v76, v158
	ds_read_b128 v[124:127], v77 offset:0
	ds_read_b128 v[128:131], v77 offset:0x2000
	v_add_u32_e32 v76, v76, v159
	ds_read_b128 v[132:135], v76 offset:0
	ds_read_b128 v[136:139], v76 offset:0x2000
	s_waitcnt lgkmcnt(4)
	s_add_i32 s3, s2, 0xbf
	s_cmp_le_i32 s3, s79
	s_setprio 1
	v_mfma_f32_32x32x16_bf16 v[84:99], v[68:71], v[100:103], 0
	v_mfma_f32_32x32x16_bf16 v[84:99], v[116:119], v[104:107], v[84:99]
	v_mfma_f32_32x32x16_bf16 v[68:83], v[72:75], v[100:103], 0
	v_mfma_f32_32x32x16_bf16 v[68:83], v[120:123], v[104:107], v[68:83]
	s_waitcnt lgkmcnt(0)
	v_mfma_f32_32x32x16_bf16 v[84:99], v[124:127], v[108:111], v[84:99]
	v_mfma_f32_32x32x16_bf16 v[84:99], v[132:135], v[112:115], v[84:99]
	v_mfma_f32_32x32x16_bf16 v[68:83], v[128:131], v[108:111], v[68:83]
	v_mfma_f32_32x32x16_bf16 v[68:83], v[136:139], v[112:115], v[68:83]
	s_setprio 0
	v_add_u32_e32 v164, s4, v160
	ds_read_b64_tr_b16 v[144:145], v164 offset:0
	ds_read_b64_tr_b16 v[146:147], v164 offset:0x800
	ds_read_b64_tr_b16 v[140:141], v164 offset:0x1000
	ds_read_b64_tr_b16 v[142:143], v164 offset:0x1800
	ds_read_b64_tr_b16 v[136:137], v164 offset:0x2000
	ds_read_b64_tr_b16 v[138:139], v164 offset:0x2800
	ds_read_b64_tr_b16 v[132:133], v164 offset:0x3000
	ds_read_b64_tr_b16 v[134:135], v164 offset:0x3800
	ds_read_b64_tr_b16 v[128:129], v164 offset:0x200
	ds_read_b64_tr_b16 v[130:131], v164 offset:0xa00
	ds_read_b64_tr_b16 v[124:125], v164 offset:0x1200
	ds_read_b64_tr_b16 v[126:127], v164 offset:0x1a00
	ds_read_b64_tr_b16 v[120:121], v164 offset:0x2200
	ds_read_b64_tr_b16 v[122:123], v164 offset:0x2a00
	ds_read_b64_tr_b16 v[116:117], v164 offset:0x3200
	ds_read_b64_tr_b16 v[118:119], v164 offset:0x3a00
	s_cbranch_scc1 .LBB0_957
	v_add_u32_e32 v165, 64, v161
	v_cmp_gt_i32_e64 s[70:71], 22, v165
	v_cmp_gt_i32_e64 s[72:73], 23, v165
	v_cmp_gt_i32_e64 s[68:69], 21, v165
	s_and_b64 s[70:71], s[72:73], s[70:71]
	v_cmp_gt_i32_e64 s[66:67], 20, v165
	s_and_b64 s[68:69], s[70:71], s[68:69]
	v_cmp_gt_i32_e64 s[64:65], 19, v165
	s_and_b64 s[66:67], s[68:69], s[66:67]
	v_cmp_gt_i32_e64 s[62:63], 18, v165
	s_and_b64 s[64:65], s[66:67], s[64:65]
	v_cmp_gt_i32_e64 s[60:61], 17, v165
	s_and_b64 s[62:63], s[64:65], s[62:63]
	v_cmp_gt_i32_e64 s[58:59], 16, v165
	s_and_b64 s[60:61], s[62:63], s[60:61]
	v_cmp_gt_i32_e64 s[56:57], 7, v165
	s_and_b64 s[58:59], s[60:61], s[58:59]
	v_cmp_gt_i32_e64 s[54:55], 6, v165
	s_and_b64 s[56:57], s[58:59], s[56:57]
	v_cmp_gt_i32_e64 s[52:53], 5, v165
	s_and_b64 s[54:55], s[56:57], s[54:55]
	v_cmp_gt_i32_e64 s[50:51], 4, v165
	s_and_b64 s[52:53], s[54:55], s[52:53]
	v_cmp_gt_i32_e64 s[48:49], 3, v165
	s_and_b64 s[50:51], s[52:53], s[50:51]
	v_cmp_gt_i32_e64 s[46:47], 2, v165
	s_and_b64 s[48:49], s[50:51], s[48:49]
	v_cmp_gt_i32_e64 s[44:45], 1, v165
	s_and_b64 s[46:47], s[48:49], s[46:47]
	v_cmp_gt_i32_e64 s[42:43], 0, v165
	s_and_b64 s[44:45], s[46:47], s[44:45]
	s_and_b64 s[42:43], s[44:45], s[42:43]
	v_cmp_gt_i32_e64 s[40:41], 54, v165
	v_cndmask_b32_e64 v84, v84, v204, s[42:43]
	v_cmp_gt_i32_e64 s[42:43], 55, v165
	v_cmp_gt_i32_e64 s[38:39], 53, v165
	s_and_b64 s[40:41], s[42:43], s[40:41]
	v_cmp_gt_i32_e64 s[36:37], 52, v165
	s_and_b64 s[38:39], s[40:41], s[38:39]
	v_cmp_gt_i32_e64 s[34:35], 51, v165
	s_and_b64 s[36:37], s[38:39], s[36:37]
	v_cmp_gt_i32_e64 s[30:31], 50, v165
	s_and_b64 s[34:35], s[36:37], s[34:35]
	v_cmp_gt_i32_e64 s[28:29], 49, v165
	s_and_b64 s[30:31], s[34:35], s[30:31]
	v_cmp_gt_i32_e64 s[26:27], 48, v165
	s_and_b64 s[28:29], s[30:31], s[28:29]
	v_cmp_gt_i32_e64 s[24:25], 39, v165
	s_and_b64 s[26:27], s[28:29], s[26:27]
	v_cmp_gt_i32_e64 s[22:23], 38, v165
	s_and_b64 s[24:25], s[26:27], s[24:25]
	v_cmp_gt_i32_e64 s[20:21], 37, v165
	s_and_b64 s[22:23], s[24:25], s[22:23]
	v_cmp_gt_i32_e64 s[18:19], 36, v165
	s_and_b64 s[20:21], s[22:23], s[20:21]
	v_cmp_gt_i32_e64 s[16:17], 35, v165
	s_and_b64 s[18:19], s[20:21], s[18:19]
	v_cmp_gt_i32_e64 s[14:15], 34, v165
	s_and_b64 s[16:17], s[18:19], s[16:17]
	v_cmp_gt_i32_e64 s[12:13], 33, v165
	s_and_b64 s[14:15], s[16:17], s[14:15]
	v_cmp_gt_i32_e32 vcc, 32, v165
	s_and_b64 s[12:13], s[14:15], s[12:13]
	s_and_b64 vcc, s[12:13], vcc
	v_cndmask_b32_e64 v99, v99, v204, s[72:73]
	v_cndmask_b32_e64 v98, v98, v204, s[70:71]
	v_cndmask_b32_e64 v97, v97, v204, s[68:69]
	v_cndmask_b32_e64 v96, v96, v204, s[66:67]
	v_cndmask_b32_e64 v95, v95, v204, s[64:65]
	v_cndmask_b32_e64 v94, v94, v204, s[62:63]
	v_cndmask_b32_e64 v93, v93, v204, s[60:61]
	v_cndmask_b32_e64 v92, v92, v204, s[58:59]
	v_cndmask_b32_e64 v91, v91, v204, s[56:57]
	v_cndmask_b32_e64 v90, v90, v204, s[54:55]
	v_cndmask_b32_e64 v89, v89, v204, s[52:53]
	v_cndmask_b32_e64 v88, v88, v204, s[50:51]
	v_cndmask_b32_e64 v87, v87, v204, s[48:49]
	v_cndmask_b32_e64 v86, v86, v204, s[46:47]
	v_cndmask_b32_e64 v85, v85, v204, s[44:45]
	v_cndmask_b32_e64 v83, v83, v204, s[42:43]
	v_cndmask_b32_e64 v82, v82, v204, s[40:41]
	v_cndmask_b32_e64 v81, v81, v204, s[38:39]
	v_cndmask_b32_e64 v80, v80, v204, s[36:37]
	v_cndmask_b32_e64 v79, v79, v204, s[34:35]
	v_cndmask_b32_e64 v78, v78, v204, s[30:31]
	v_cndmask_b32_e64 v77, v77, v204, s[28:29]
	v_cndmask_b32_e64 v76, v76, v204, s[26:27]
	v_cndmask_b32_e64 v75, v75, v204, s[24:25]
	v_cndmask_b32_e64 v74, v74, v204, s[22:23]
	v_cndmask_b32_e64 v73, v73, v204, s[20:21]
	v_cndmask_b32_e64 v72, v72, v204, s[18:19]
	v_cndmask_b32_e64 v71, v71, v204, s[16:17]
	v_cndmask_b32_e64 v70, v70, v204, s[14:15]
	v_cndmask_b32_e64 v69, v69, v204, s[12:13]
	v_cndmask_b32_e32 v68, v68, v204, vcc
